# grid barriers 2-14: unreachable XCD-census block (st[0] is nonzero after barrier 1) removed, arrival path is straight-line; code 14 KiB smaller
# speedup vs baseline: 1.0045x; 1.0045x over previous
; DI int fresh_tid() { int t = threadIdx.x; asm volatile("" : "+v"(t)); return t; }
; DI unsigned xb_ld(unsigned* p)              { return __hip_atomic_load(p, __ATOMIC_RELAXED, __HIP_MEMORY_SCOPE_AGENT); }
; DI unsigned xb_add(unsigned* p, unsigned v) { return __hip_atomic_fetch_add(p, v, __ATOMIC_RELAXED, __HIP_MEMORY_SCOPE_AGENT); }
; DI unsigned xb_xcc_id() { return (unsigned)__builtin_amdgcn_s_getreg((3 << 11) | 20) & 0xFu; }
; DI void xcd_barrier_complete(unsigned* bar, unsigned x, unsigned& nloc, unsigned& nx) {
;     const unsigned G = gridDim.x;
;     unsigned sum, cnt, mine, sp = 0u;
;     for (;;) {
;         sum = 0u; cnt = 0u; mine = 0u;
; #pragma unroll
;         for (unsigned j = 0; j < 16; ++j) { const unsigned c = xb_ld(&bar[XB_XCNT(j)]); sum += c; cnt += (c > 0u) ? 1u : 0u; mine = (j == x) ? c : mine; }
;         if (sum == G) break;
;         __builtin_amdgcn_s_sleep(1);
;         if ((++sp & 255u) == 0u) { if (xb_ld(&bar[XB_TMO])) break; if (sp > XB_SPIN_CAP) { atomicAdd(&bar[XB_TMO], 1u); break; } }
;     }
;     nloc = mine > 0u ? mine : 1u; nx = cnt > 0u ? cnt : 1u;
; DI void xcd_barrier(unsigned* bar, volatile __attribute__((address_space(3))) unsigned* st) {
;     ...
;     if (fresh_tid() == 0) {
;         __builtin_amdgcn_s_waitcnt(0);
;         const unsigned x = xb_xcc_id();
;         unsigned nloc = st[0], nx = st[1];
;         if (nloc == 0u) { xcd_barrier_complete(bar, x, nloc, nx); st[0] = nloc; st[1] = nx; }
;         const unsigned old = xb_add(&bar[XB_XSUB(x)], 1u);
.Lcpf_s2:
	s_or_b64 exec, exec, s[0:1]
	s_nop 0
	v_cmp_eq_u32_e32 vcc, 0, v0
	s_and_saveexec_b64 s[0:1], vcc
	s_cbranch_execz .LBB0_274
	v_mov_b32_e32 v0, 0
	s_waitcnt vmcnt(0) expcnt(0) lgkmcnt(0)
	s_getreg_b32 s3, hwreg(HW_REG_XCC_ID, 0, 4)
	ds_read_b32 v2, v0
	ds_read_b32 v1, v0 offset:4
	s_and_b32 s3, s3, 15
	s_waitcnt lgkmcnt(1)
.LBB0_238:
	s_mov_b64 s[8:9], exec
	s_lshl_b32 s3, s3, 8
	v_readlane_b32 s6, v254, 2
	v_mbcnt_lo_u32_b32 v0, s8, 0
	v_readlane_b32 s7, v254, 3
	s_add_u32 s6, s6, s3
	v_mbcnt_hi_u32_b32 v0, s9, v0
	s_addc_u32 s7, s7, 0
	v_cmp_eq_u32_e32 vcc, 0, v0
	s_and_saveexec_b64 s[10:11], vcc
	s_cbranch_execz .LBB0_240
	s_bcnt1_i32_b64 s3, s[8:9]
	v_mov_b32_e32 v3, 0x1000
	v_mov_b32_e32 v4, s3
	global_atomic_add v3, v3, v4, s[6:7] offset:1024 sc0

; DI int fresh_tid() { int t = threadIdx.x; asm volatile("" : "+v"(t)); return t; }
; DI unsigned xb_add(unsigned* p, unsigned v) { return __hip_atomic_fetch_add(p, v, __ATOMIC_RELAXED, __HIP_MEMORY_SCOPE_AGENT); }
; DI unsigned xb_xcc_id() { return (unsigned)__builtin_amdgcn_s_getreg((3 << 11) | 20) & 0xFu; }
; DI void xcd_barrier(unsigned* bar, volatile __attribute__((address_space(3))) unsigned* st) {
;     ...
;     if (fresh_tid() == 0) {
;         __builtin_amdgcn_s_waitcnt(0);
;         const unsigned x = xb_xcc_id();
;         unsigned nloc = st[0], nx = st[1];
;         if (nloc == 0u) { xcd_barrier_complete(bar, x, nloc, nx); st[0] = nloc; st[1] = nx; }
;         const unsigned old = xb_add(&bar[XB_XSUB(x)], 1u);
.Lcpf_s3:
	s_or_b64 exec, exec, s[0:1]
	s_nop 0
	v_cmp_eq_u32_e32 vcc, 0, v0
	s_and_saveexec_b64 s[0:1], vcc
	s_cbranch_execz .LBB0_357
	v_mov_b32_e32 v0, 0
	s_waitcnt vmcnt(0) expcnt(0) lgkmcnt(0)
	s_getreg_b32 s3, hwreg(HW_REG_XCC_ID, 0, 4)
	ds_read_b32 v2, v0
	ds_read_b32 v1, v0 offset:4
	s_and_b32 s3, s3, 15
	s_waitcnt lgkmcnt(1)
.LBB0_321:
	s_mov_b64 s[8:9], exec
	s_lshl_b32 s3, s3, 8
	v_readlane_b32 s6, v254, 2
	v_mbcnt_lo_u32_b32 v0, s8, 0
	v_readlane_b32 s7, v254, 3
	s_add_u32 s6, s6, s3
	v_mbcnt_hi_u32_b32 v0, s9, v0
	s_addc_u32 s7, s7, 0
	v_cmp_eq_u32_e32 vcc, 0, v0
	s_and_saveexec_b64 s[10:11], vcc
	s_cbranch_execz .LBB0_323
	s_bcnt1_i32_b64 s3, s[8:9]
	v_mov_b32_e32 v3, 0x1000
	v_mov_b32_e32 v4, s3
	global_atomic_add v3, v3, v4, s[6:7] offset:1024 sc0

; DI int fresh_tid() { int t = threadIdx.x; asm volatile("" : "+v"(t)); return t; }
; DI unsigned xb_add(unsigned* p, unsigned v) { return __hip_atomic_fetch_add(p, v, __ATOMIC_RELAXED, __HIP_MEMORY_SCOPE_AGENT); }
; DI unsigned xb_xcc_id() { return (unsigned)__builtin_amdgcn_s_getreg((3 << 11) | 20) & 0xFu; }
; DI void xcd_barrier(unsigned* bar, volatile __attribute__((address_space(3))) unsigned* st) {
;     ...
;     if (fresh_tid() == 0) {
;         __builtin_amdgcn_s_waitcnt(0);
;         const unsigned x = xb_xcc_id();
;         unsigned nloc = st[0], nx = st[1];
;         if (nloc == 0u) { xcd_barrier_complete(bar, x, nloc, nx); st[0] = nloc; st[1] = nx; }
;         const unsigned old = xb_add(&bar[XB_XSUB(x)], 1u);
;         const unsigned gen = old / nloc;
.Lcpf_s4:
	s_or_b64 exec, exec, s[0:1]
	s_nop 0
	v_cmp_eq_u32_e32 vcc, 0, v0
	s_and_saveexec_b64 s[0:1], vcc
	s_cbranch_execz .LBB0_434
	v_mov_b32_e32 v0, 0
	s_waitcnt vmcnt(0) expcnt(0) lgkmcnt(0)
	s_getreg_b32 s3, hwreg(HW_REG_XCC_ID, 0, 4)
	ds_read_b32 v2, v0
	ds_read_b32 v1, v0 offset:4
	s_and_b32 s3, s3, 15
	s_waitcnt lgkmcnt(1)
.LBB0_398:
	s_mov_b64 s[6:7], exec
	s_lshl_b32 s3, s3, 8
	v_readlane_b32 s4, v254, 2
	v_mbcnt_lo_u32_b32 v0, s6, 0
	v_readlane_b32 s5, v254, 3
	s_add_u32 s4, s4, s3
	v_mbcnt_hi_u32_b32 v0, s7, v0
	s_addc_u32 s5, s5, 0
	v_cmp_eq_u32_e32 vcc, 0, v0
	s_and_saveexec_b64 s[8:9], vcc
	s_cbranch_execz .LBB0_400
	s_bcnt1_i32_b64 s3, s[6:7]
	v_mov_b32_e32 v3, 0x1000
	v_mov_b32_e32 v4, s3
	global_atomic_add v3, v3, v4, s[4:5] offset:1024 sc0

; DI int fresh_tid() { int t = threadIdx.x; asm volatile("" : "+v"(t)); return t; }
; DI unsigned xb_add(unsigned* p, unsigned v) { return __hip_atomic_fetch_add(p, v, __ATOMIC_RELAXED, __HIP_MEMORY_SCOPE_AGENT); }
; DI unsigned xb_xcc_id() { return (unsigned)__builtin_amdgcn_s_getreg((3 << 11) | 20) & 0xFu; }
; DI void xcd_barrier(unsigned* bar, volatile __attribute__((address_space(3))) unsigned* st) {
;     ...
;     if (fresh_tid() == 0) {
;         __builtin_amdgcn_s_waitcnt(0);
;         const unsigned x = xb_xcc_id();
;         unsigned nloc = st[0], nx = st[1];
;         if (nloc == 0u) { xcd_barrier_complete(bar, x, nloc, nx); st[0] = nloc; st[1] = nx; }
;         const unsigned old = xb_add(&bar[XB_XSUB(x)], 1u);
;         const unsigned gen = old / nloc;
.Lcpf_s5:
	s_or_b64 exec, exec, s[0:1]
	s_nop 0
	v_cmp_eq_u32_e32 vcc, 0, v0
	s_and_saveexec_b64 s[0:1], vcc
	s_cbranch_execz .LBB0_524
	v_mov_b32_e32 v0, 0
	s_waitcnt vmcnt(0) expcnt(0) lgkmcnt(0)
	s_getreg_b32 s3, hwreg(HW_REG_XCC_ID, 0, 4)
	ds_read_b32 v2, v0
	ds_read_b32 v1, v0 offset:4
	s_and_b32 s3, s3, 15
	s_waitcnt lgkmcnt(1)
.LBB0_488:
	s_mov_b64 s[8:9], exec
	s_lshl_b32 s3, s3, 8
	v_readlane_b32 s4, v254, 2
	v_mbcnt_lo_u32_b32 v0, s8, 0
	v_readlane_b32 s5, v254, 3
	s_add_u32 s4, s4, s3
	v_mbcnt_hi_u32_b32 v0, s9, v0
	s_addc_u32 s5, s5, 0
	v_cmp_eq_u32_e32 vcc, 0, v0
	s_and_saveexec_b64 s[10:11], vcc
	s_cbranch_execz .LBB0_490
	s_bcnt1_i32_b64 s3, s[8:9]
	v_mov_b32_e32 v3, 0x1000
	v_mov_b32_e32 v4, s3
	global_atomic_add v3, v3, v4, s[4:5] offset:1024 sc0

; DI int fresh_tid() { int t = threadIdx.x; asm volatile("" : "+v"(t)); return t; }
; DI unsigned xb_add(unsigned* p, unsigned v) { return __hip_atomic_fetch_add(p, v, __ATOMIC_RELAXED, __HIP_MEMORY_SCOPE_AGENT); }
; DI unsigned xb_xcc_id() { return (unsigned)__builtin_amdgcn_s_getreg((3 << 11) | 20) & 0xFu; }
; DI void xcd_barrier(unsigned* bar, volatile __attribute__((address_space(3))) unsigned* st) {
;     ...
;     if (fresh_tid() == 0) {
;         __builtin_amdgcn_s_waitcnt(0);
;         const unsigned x = xb_xcc_id();
;         unsigned nloc = st[0], nx = st[1];
;         if (nloc == 0u) { xcd_barrier_complete(bar, x, nloc, nx); st[0] = nloc; st[1] = nx; }
;         const unsigned old = xb_add(&bar[XB_XSUB(x)], 1u);
;         const unsigned gen = old / nloc;
.Lcpf_s6:
	s_or_b64 exec, exec, s[0:1]
	s_nop 0
	v_cmp_eq_u32_e32 vcc, 0, v0
	s_and_saveexec_b64 s[0:1], vcc
	s_cbranch_execz .LBB0_632
	v_mov_b32_e32 v0, 0
	s_waitcnt vmcnt(0) expcnt(0) lgkmcnt(0)
	s_getreg_b32 s3, hwreg(HW_REG_XCC_ID, 0, 4)
	ds_read_b32 v2, v0
	ds_read_b32 v1, v0 offset:4
	s_and_b32 s3, s3, 15
	s_waitcnt lgkmcnt(1)
.LBB0_596:
	s_mov_b64 s[6:7], exec
	s_lshl_b32 s3, s3, 8
	v_readlane_b32 s4, v254, 2
	v_mbcnt_lo_u32_b32 v0, s6, 0
	v_readlane_b32 s5, v254, 3
	s_add_u32 s4, s4, s3
	v_mbcnt_hi_u32_b32 v0, s7, v0
	s_addc_u32 s5, s5, 0
	v_cmp_eq_u32_e32 vcc, 0, v0
	s_and_saveexec_b64 s[8:9], vcc
	s_cbranch_execz .LBB0_598
	s_bcnt1_i32_b64 s3, s[6:7]
	v_mov_b32_e32 v3, 0x1000
	v_mov_b32_e32 v4, s3
	global_atomic_add v3, v3, v4, s[4:5] offset:1024 sc0

; DI int fresh_tid() { int t = threadIdx.x; asm volatile("" : "+v"(t)); return t; }
; DI unsigned xb_add(unsigned* p, unsigned v) { return __hip_atomic_fetch_add(p, v, __ATOMIC_RELAXED, __HIP_MEMORY_SCOPE_AGENT); }
; DI unsigned xb_xcc_id() { return (unsigned)__builtin_amdgcn_s_getreg((3 << 11) | 20) & 0xFu; }
; DI void xcd_barrier(unsigned* bar, volatile __attribute__((address_space(3))) unsigned* st) {
;     ...
;     if (fresh_tid() == 0) {
;         __builtin_amdgcn_s_waitcnt(0);
;         const unsigned x = xb_xcc_id();
;         unsigned nloc = st[0], nx = st[1];
;         if (nloc == 0u) { xcd_barrier_complete(bar, x, nloc, nx); st[0] = nloc; st[1] = nx; }
;         const unsigned old = xb_add(&bar[XB_XSUB(x)], 1u);
;         const unsigned gen = old / nloc;
.Lcpf_s7:
	s_or_b64 exec, exec, s[0:1]
	s_nop 0
	v_cmp_eq_u32_e32 vcc, 0, v0
	s_and_saveexec_b64 s[0:1], vcc
	s_cbranch_execz .LBB0_714
	v_mov_b32_e32 v0, 0
	s_waitcnt vmcnt(0) expcnt(0) lgkmcnt(0)
	s_getreg_b32 s3, hwreg(HW_REG_XCC_ID, 0, 4)
	ds_read_b32 v2, v0
	ds_read_b32 v1, v0 offset:4
	s_and_b32 s3, s3, 15
	s_waitcnt lgkmcnt(1)
.LBB0_678:
	s_mov_b64 s[6:7], exec
	s_lshl_b32 s3, s3, 8
	v_readlane_b32 s4, v254, 2
	v_mbcnt_lo_u32_b32 v0, s6, 0
	v_readlane_b32 s5, v254, 3
	s_add_u32 s4, s4, s3
	v_mbcnt_hi_u32_b32 v0, s7, v0
	s_addc_u32 s5, s5, 0
	v_cmp_eq_u32_e32 vcc, 0, v0
	s_and_saveexec_b64 s[8:9], vcc
	s_cbranch_execz .LBB0_680
	s_bcnt1_i32_b64 s3, s[6:7]
	v_mov_b32_e32 v3, 0x1000
	v_mov_b32_e32 v4, s3
	global_atomic_add v3, v3, v4, s[4:5] offset:1024 sc0

; DI int fresh_tid() { int t = threadIdx.x; asm volatile("" : "+v"(t)); return t; }
; DI unsigned xb_add(unsigned* p, unsigned v) { return __hip_atomic_fetch_add(p, v, __ATOMIC_RELAXED, __HIP_MEMORY_SCOPE_AGENT); }
; DI unsigned xb_xcc_id() { return (unsigned)__builtin_amdgcn_s_getreg((3 << 11) | 20) & 0xFu; }
; DI void xcd_barrier(unsigned* bar, volatile __attribute__((address_space(3))) unsigned* st) {
;     ...
;     if (fresh_tid() == 0) {
;         __builtin_amdgcn_s_waitcnt(0);
;         const unsigned x = xb_xcc_id();
;         unsigned nloc = st[0], nx = st[1];
;         if (nloc == 0u) { xcd_barrier_complete(bar, x, nloc, nx); st[0] = nloc; st[1] = nx; }
;         const unsigned old = xb_add(&bar[XB_XSUB(x)], 1u);
;         const unsigned gen = old / nloc;
.Lcpf_s8:
	s_or_b64 exec, exec, s[0:1]
	s_nop 0
	v_cmp_eq_u32_e32 vcc, 0, v0
	s_and_saveexec_b64 s[0:1], vcc
	v_readlane_b32 s96, v254, 62
	v_readlane_b32 s97, v254, 63
	s_cbranch_execz .LBB0_835
	v_mov_b32_e32 v0, 0
	s_waitcnt vmcnt(0) expcnt(0) lgkmcnt(0)
	s_getreg_b32 s3, hwreg(HW_REG_XCC_ID, 0, 4)
	ds_read_b32 v2, v0
	ds_read_b32 v1, v0 offset:4
	s_and_b32 s3, s3, 15
	s_waitcnt lgkmcnt(1)
.LBB0_799:
	s_mov_b64 s[6:7], exec
	s_lshl_b32 s3, s3, 8
	v_readlane_b32 s4, v254, 2
	v_mbcnt_lo_u32_b32 v0, s6, 0
	v_readlane_b32 s5, v254, 3
	s_add_u32 s4, s4, s3
	v_mbcnt_hi_u32_b32 v0, s7, v0
	s_addc_u32 s5, s5, 0
	v_cmp_eq_u32_e32 vcc, 0, v0
	s_and_saveexec_b64 s[8:9], vcc
	s_cbranch_execz .LBB0_801
	s_bcnt1_i32_b64 s3, s[6:7]
	v_mov_b32_e32 v3, 0x1000
	v_mov_b32_e32 v4, s3
	global_atomic_add v3, v3, v4, s[4:5] offset:1024 sc0

; DI int fresh_tid() { int t = threadIdx.x; asm volatile("" : "+v"(t)); return t; }
; DI unsigned xb_add(unsigned* p, unsigned v) { return __hip_atomic_fetch_add(p, v, __ATOMIC_RELAXED, __HIP_MEMORY_SCOPE_AGENT); }
; DI unsigned xb_xcc_id() { return (unsigned)__builtin_amdgcn_s_getreg((3 << 11) | 20) & 0xFu; }
; DI void xcd_barrier(unsigned* bar, volatile __attribute__((address_space(3))) unsigned* st) {
;     asm volatile("s_waitcnt vmcnt(0)" ::: "memory");
;     __syncthreads();
;     if (fresh_tid() == 0) {
;         __builtin_amdgcn_s_waitcnt(0);
;         const unsigned x = xb_xcc_id();
;         unsigned nloc = st[0], nx = st[1];
;         if (nloc == 0u) { xcd_barrier_complete(bar, x, nloc, nx); st[0] = nloc; st[1] = nx; }
;         const unsigned old = xb_add(&bar[XB_XSUB(x)], 1u);
;         const unsigned gen = old / nloc;
.LBB0_859:
	s_waitcnt vmcnt(0)
	v_mov_b32_e32 v0, v250
	s_barrier
	s_getpc_b64 vcc
	v_mov_b32_e32 v2, vcc_lo
	v_mov_b32_e32 v3, vcc_hi
	v_cmp_lt_u32_e32 vcc, 63, v0
	s_and_saveexec_b64 s[4:5], vcc
	s_cbranch_execz .Lcpf_s9
	v_lshlrev_b32_e32 v1, 6, v0
	v_subrev_u32_e32 v1, 0x1000, v1
	v_min_u32_e32 v1, 0x6f80, v1
	v_add_co_u32_e32 v2, vcc, v2, v1
	s_nop 1
	v_addc_co_u32_e32 v3, vcc, 0, v3, vcc
	global_load_dword v4, v[2:3], off
.Lcpf_s9:
	s_or_b64 exec, exec, s[4:5]
	s_nop 0
	v_cmp_eq_u32_e32 vcc, 0, v0
	s_and_saveexec_b64 s[4:5], vcc
	v_readlane_b32 s50, v254, 54
	v_readlane_b32 s51, v254, 55
	s_cbranch_execz .LBB0_911
	v_mov_b32_e32 v0, 0
	s_waitcnt vmcnt(0) expcnt(0) lgkmcnt(0)
	s_getreg_b32 s3, hwreg(HW_REG_XCC_ID, 0, 4)
	ds_read_b32 v2, v0
	ds_read_b32 v1, v0 offset:4
	s_and_b32 s3, s3, 15
	s_waitcnt lgkmcnt(1)
.LBB0_875:
	s_mov_b64 s[8:9], exec
	s_lshl_b32 s3, s3, 8
	v_readlane_b32 s6, v254, 2
	v_mbcnt_lo_u32_b32 v0, s8, 0
	v_readlane_b32 s7, v254, 3
	s_add_u32 s6, s6, s3
	v_mbcnt_hi_u32_b32 v0, s9, v0
	s_addc_u32 s7, s7, 0
	v_cmp_eq_u32_e32 vcc, 0, v0
	s_and_saveexec_b64 s[10:11], vcc
	s_cbranch_execz .LBB0_877
	s_bcnt1_i32_b64 s3, s[8:9]
	v_mov_b32_e32 v3, 0x1000
	v_mov_b32_e32 v4, s3
	global_atomic_add v3, v3, v4, s[6:7] offset:1024 sc0

; DI int fresh_tid() { int t = threadIdx.x; asm volatile("" : "+v"(t)); return t; }
; DI unsigned xb_add(unsigned* p, unsigned v) { return __hip_atomic_fetch_add(p, v, __ATOMIC_RELAXED, __HIP_MEMORY_SCOPE_AGENT); }
; DI unsigned xb_xcc_id() { return (unsigned)__builtin_amdgcn_s_getreg((3 << 11) | 20) & 0xFu; }
; DI void xcd_barrier(unsigned* bar, volatile __attribute__((address_space(3))) unsigned* st) {
;     asm volatile("s_waitcnt vmcnt(0)" ::: "memory");
;     __syncthreads();
;     if (fresh_tid() == 0) {
;         __builtin_amdgcn_s_waitcnt(0);
;         const unsigned x = xb_xcc_id();
;         unsigned nloc = st[0], nx = st[1];
;         if (nloc == 0u) { xcd_barrier_complete(bar, x, nloc, nx); st[0] = nloc; st[1] = nx; }
;         const unsigned old = xb_add(&bar[XB_XSUB(x)], 1u);
;         const unsigned gen = old / nloc;
.LBB0_935:
	s_waitcnt vmcnt(0)
	v_mov_b32_e32 v0, v250
	s_barrier
	s_getpc_b64 vcc
	v_mov_b32_e32 v2, vcc_lo
	v_mov_b32_e32 v3, vcc_hi
	v_cmp_lt_u32_e32 vcc, 63, v0
	s_and_saveexec_b64 s[4:5], vcc
	s_cbranch_execz .Lcpf_s10
	v_lshlrev_b32_e32 v1, 6, v0
	v_subrev_u32_e32 v1, 0x1000, v1
	v_min_u32_e32 v1, 0x5bc0, v1
	v_add_co_u32_e32 v2, vcc, v2, v1
	s_nop 1
	v_addc_co_u32_e32 v3, vcc, 0, v3, vcc
	global_load_dword v4, v[2:3], off
.Lcpf_s10:
	s_or_b64 exec, exec, s[4:5]
	s_nop 0
	v_cmp_eq_u32_e32 vcc, 0, v0
	s_and_saveexec_b64 s[4:5], vcc
	s_cbranch_execz .LBB0_987
	v_mov_b32_e32 v0, 0
	s_waitcnt vmcnt(0) expcnt(0) lgkmcnt(0)
	s_getreg_b32 s3, hwreg(HW_REG_XCC_ID, 0, 4)
	ds_read_b32 v2, v0
	ds_read_b32 v1, v0 offset:4
	s_and_b32 s3, s3, 15
	s_waitcnt lgkmcnt(1)
.LBB0_951:
	s_mov_b64 s[8:9], exec
	s_lshl_b32 s3, s3, 8
	v_readlane_b32 s6, v254, 2
	v_mbcnt_lo_u32_b32 v0, s8, 0
	v_readlane_b32 s7, v254, 3
	s_add_u32 s6, s6, s3
	v_mbcnt_hi_u32_b32 v0, s9, v0
	s_addc_u32 s7, s7, 0
	v_cmp_eq_u32_e32 vcc, 0, v0
	s_and_saveexec_b64 s[10:11], vcc
	s_cbranch_execz .LBB0_953
	s_bcnt1_i32_b64 s3, s[8:9]
	v_mov_b32_e32 v3, 0x1000
	v_mov_b32_e32 v4, s3
	global_atomic_add v3, v3, v4, s[6:7] offset:1024 sc0

; DI int fresh_tid() { int t = threadIdx.x; asm volatile("" : "+v"(t)); return t; }
; DI unsigned xb_add(unsigned* p, unsigned v) { return __hip_atomic_fetch_add(p, v, __ATOMIC_RELAXED, __HIP_MEMORY_SCOPE_AGENT); }
; DI unsigned xb_xcc_id() { return (unsigned)__builtin_amdgcn_s_getreg((3 << 11) | 20) & 0xFu; }
; DI void xcd_barrier(unsigned* bar, volatile __attribute__((address_space(3))) unsigned* st) {
;     asm volatile("s_waitcnt vmcnt(0)" ::: "memory");
;     __syncthreads();
;     if (fresh_tid() == 0) {
;         __builtin_amdgcn_s_waitcnt(0);
;         const unsigned x = xb_xcc_id();
;         unsigned nloc = st[0], nx = st[1];
;         if (nloc == 0u) { xcd_barrier_complete(bar, x, nloc, nx); st[0] = nloc; st[1] = nx; }
;         const unsigned old = xb_add(&bar[XB_XSUB(x)], 1u);
;         const unsigned gen = old / nloc;
.LBB0_998:
	s_or_b64 exec, exec, s[6:7]
	s_waitcnt vmcnt(0)
	v_mov_b32_e32 v0, v250
	s_barrier
	s_getpc_b64 vcc
	v_mov_b32_e32 v2, vcc_lo
	v_mov_b32_e32 v3, vcc_hi
	v_cmp_lt_u32_e32 vcc, 63, v0
	s_and_saveexec_b64 s[4:5], vcc
	s_cbranch_execz .Lcpf_s11
	v_lshlrev_b32_e32 v1, 6, v0
	v_subrev_u32_e32 v1, 0x1000, v1
	v_min_u32_e32 v1, 0x4680, v1
	v_add_co_u32_e32 v2, vcc, v2, v1
	s_nop 1
	v_addc_co_u32_e32 v3, vcc, 0, v3, vcc
	global_load_dword v4, v[2:3], off
.Lcpf_s11:
	s_or_b64 exec, exec, s[4:5]
	s_nop 0
	v_cmp_eq_u32_e32 vcc, 0, v0
	s_and_saveexec_b64 s[4:5], vcc
	v_readlane_b32 s12, v254, 20
	v_readlane_b32 s26, v254, 34
	v_readlane_b32 s27, v254, 35
	v_readlane_b32 s24, v254, 32
	v_readlane_b32 s25, v254, 33
	s_mov_b64 s[78:79], s[26:27]
	s_mov_b64 s[76:77], s[24:25]
	v_readlane_b32 s13, v254, 21
	v_readlane_b32 s14, v254, 22
	v_readlane_b32 s15, v254, 23
	v_readlane_b32 s16, v254, 24
	v_readlane_b32 s17, v254, 25
	v_readlane_b32 s18, v254, 26
	v_readlane_b32 s19, v254, 27
	v_readlane_b32 s20, v254, 28
	v_readlane_b32 s21, v254, 29
	v_readlane_b32 s22, v254, 30
	v_readlane_b32 s23, v254, 31
	s_cbranch_execz .LBB0_1050
	v_mov_b32_e32 v0, 0
	s_waitcnt vmcnt(0) expcnt(0) lgkmcnt(0)
	s_getreg_b32 s3, hwreg(HW_REG_XCC_ID, 0, 4)
	ds_read_b32 v2, v0
	ds_read_b32 v1, v0 offset:4
	s_and_b32 s3, s3, 15
	s_waitcnt lgkmcnt(1)
.LBB0_1014:
	s_mov_b64 s[8:9], exec
	s_lshl_b32 s3, s3, 8
	v_readlane_b32 s6, v254, 2
	v_mbcnt_lo_u32_b32 v0, s8, 0
	v_readlane_b32 s7, v254, 3
	s_add_u32 s6, s6, s3
	v_mbcnt_hi_u32_b32 v0, s9, v0
	s_addc_u32 s7, s7, 0
	v_cmp_eq_u32_e32 vcc, 0, v0
	s_and_saveexec_b64 s[12:13], vcc
	s_cbranch_execz .LBB0_1016
	s_bcnt1_i32_b64 s3, s[8:9]
	v_mov_b32_e32 v3, 0x1000
	v_mov_b32_e32 v4, s3
	global_atomic_add v3, v3, v4, s[6:7] offset:1024 sc0

; DI int fresh_tid() { int t = threadIdx.x; asm volatile("" : "+v"(t)); return t; }
; DI unsigned xb_add(unsigned* p, unsigned v) { return __hip_atomic_fetch_add(p, v, __ATOMIC_RELAXED, __HIP_MEMORY_SCOPE_AGENT); }
; DI unsigned xb_xcc_id() { return (unsigned)__builtin_amdgcn_s_getreg((3 << 11) | 20) & 0xFu; }
; DI void xcd_barrier(unsigned* bar, volatile __attribute__((address_space(3))) unsigned* st) {
;     asm volatile("s_waitcnt vmcnt(0)" ::: "memory");
;     __syncthreads();
;     if (fresh_tid() == 0) {
;         __builtin_amdgcn_s_waitcnt(0);
;         const unsigned x = xb_xcc_id();
;         unsigned nloc = st[0], nx = st[1];
;         if (nloc == 0u) { xcd_barrier_complete(bar, x, nloc, nx); st[0] = nloc; st[1] = nx; }
;         const unsigned old = xb_add(&bar[XB_XSUB(x)], 1u);
;         const unsigned gen = old / nloc;
.LBB0_1092:
	s_waitcnt vmcnt(0)
	v_mov_b32_e32 v0, v250
	s_barrier
	s_getpc_b64 vcc
	v_mov_b32_e32 v2, vcc_lo
	v_mov_b32_e32 v3, vcc_hi
	v_cmp_lt_u32_e32 vcc, 63, v0
	s_and_saveexec_b64 s[4:5], vcc
	s_cbranch_execz .Lcpf_s12
	v_lshlrev_b32_e32 v1, 6, v0
	v_subrev_u32_e32 v1, 0x1000, v1
	v_min_u32_e32 v1, 0x26c0, v1
	v_add_co_u32_e32 v2, vcc, v2, v1
	s_nop 1
	v_addc_co_u32_e32 v3, vcc, 0, v3, vcc
	global_load_dword v4, v[2:3], off
.Lcpf_s12:
	s_or_b64 exec, exec, s[4:5]
	s_nop 0
	v_cmp_eq_u32_e32 vcc, 0, v0
	s_and_saveexec_b64 s[4:5], vcc
	s_cbranch_execz .LBB0_1144
	v_mov_b32_e32 v0, 0
	s_waitcnt vmcnt(0) expcnt(0) lgkmcnt(0)
	s_getreg_b32 s3, hwreg(HW_REG_XCC_ID, 0, 4)
	ds_read_b32 v2, v0
	ds_read_b32 v1, v0 offset:4
	s_and_b32 s3, s3, 15
	s_waitcnt lgkmcnt(1)
.LBB0_1108:
	s_mov_b64 s[8:9], exec
	s_lshl_b32 s3, s3, 8
	v_readlane_b32 s6, v254, 2
	v_mbcnt_lo_u32_b32 v0, s8, 0
	v_readlane_b32 s7, v254, 3
	s_add_u32 s6, s6, s3
	v_mbcnt_hi_u32_b32 v0, s9, v0
	s_addc_u32 s7, s7, 0
	v_cmp_eq_u32_e32 vcc, 0, v0
	s_and_saveexec_b64 s[16:17], vcc
	s_cbranch_execz .LBB0_1110
	s_bcnt1_i32_b64 s3, s[8:9]
	v_mov_b32_e32 v3, 0x1000
	v_mov_b32_e32 v4, s3
	global_atomic_add v3, v3, v4, s[6:7] offset:1024 sc0

; DI int fresh_tid() { int t = threadIdx.x; asm volatile("" : "+v"(t)); return t; }
; DI unsigned xb_add(unsigned* p, unsigned v) { return __hip_atomic_fetch_add(p, v, __ATOMIC_RELAXED, __HIP_MEMORY_SCOPE_AGENT); }
; DI unsigned xb_xcc_id() { return (unsigned)__builtin_amdgcn_s_getreg((3 << 11) | 20) & 0xFu; }
; DI void xcd_barrier(unsigned* bar, volatile __attribute__((address_space(3))) unsigned* st) {
;     asm volatile("s_waitcnt vmcnt(0)" ::: "memory");
;     __syncthreads();
;     if (fresh_tid() == 0) {
;         __builtin_amdgcn_s_waitcnt(0);
;         const unsigned x = xb_xcc_id();
;         unsigned nloc = st[0], nx = st[1];
;         if (nloc == 0u) { xcd_barrier_complete(bar, x, nloc, nx); st[0] = nloc; st[1] = nx; }
;         const unsigned old = xb_add(&bar[XB_XSUB(x)], 1u);
;         const unsigned gen = old / nloc;
.LBB0_1151:
	s_or_b64 exec, exec, s[6:7]
	s_waitcnt vmcnt(0)
	v_mov_b32_e32 v0, v250
	s_barrier
	s_getpc_b64 vcc
	v_mov_b32_e32 v2, vcc_lo
	v_mov_b32_e32 v3, vcc_hi
	v_cmp_lt_u32_e32 vcc, 63, v0
	s_and_saveexec_b64 s[4:5], vcc
	s_cbranch_execz .Lcpf_s13
	v_lshlrev_b32_e32 v1, 6, v0
	v_subrev_u32_e32 v1, 0x1000, v1
	v_min_u32_e32 v1, 0x22c0, v1
	v_add_co_u32_e32 v2, vcc, v2, v1
	s_nop 1
	v_addc_co_u32_e32 v3, vcc, 0, v3, vcc
	global_load_dword v4, v[2:3], off
.Lcpf_s13:
	s_or_b64 exec, exec, s[4:5]
	s_nop 0
	v_cmp_eq_u32_e32 vcc, 0, v0
	s_and_saveexec_b64 s[4:5], vcc
	s_cbranch_execz .LBB0_1203
	v_mov_b32_e32 v0, 0
	s_waitcnt vmcnt(0) expcnt(0) lgkmcnt(0)
	s_getreg_b32 s3, hwreg(HW_REG_XCC_ID, 0, 4)
	ds_read_b32 v2, v0
	ds_read_b32 v1, v0 offset:4
	s_and_b32 s3, s3, 15
	s_waitcnt lgkmcnt(1)
.LBB0_1167:
	s_mov_b64 s[8:9], exec
	s_lshl_b32 s3, s3, 8
	v_readlane_b32 s6, v254, 2
	v_mbcnt_lo_u32_b32 v0, s8, 0
	v_readlane_b32 s7, v254, 3
	s_add_u32 s6, s6, s3
	v_mbcnt_hi_u32_b32 v0, s9, v0
	s_addc_u32 s7, s7, 0
	v_cmp_eq_u32_e32 vcc, 0, v0
	s_and_saveexec_b64 s[12:13], vcc
	s_cbranch_execz .LBB0_1169
	s_bcnt1_i32_b64 s3, s[8:9]
	v_mov_b32_e32 v3, 0x1000
	v_mov_b32_e32 v4, s3
	global_atomic_add v3, v3, v4, s[6:7] offset:1024 sc0

; DI int fresh_tid() { int t = threadIdx.x; asm volatile("" : "+v"(t)); return t; }
; DI unsigned xb_add(unsigned* p, unsigned v) { return __hip_atomic_fetch_add(p, v, __ATOMIC_RELAXED, __HIP_MEMORY_SCOPE_AGENT); }
; DI unsigned xb_xcc_id() { return (unsigned)__builtin_amdgcn_s_getreg((3 << 11) | 20) & 0xFu; }
; DI void xcd_barrier(unsigned* bar, volatile __attribute__((address_space(3))) unsigned* st) {
;     asm volatile("s_waitcnt vmcnt(0)" ::: "memory");
;     __syncthreads();
;     if (fresh_tid() == 0) {
;         __builtin_amdgcn_s_waitcnt(0);
;         const unsigned x = xb_xcc_id();
;         unsigned nloc = st[0], nx = st[1];
;         if (nloc == 0u) { xcd_barrier_complete(bar, x, nloc, nx); st[0] = nloc; st[1] = nx; }
;         const unsigned old = xb_add(&bar[XB_XSUB(x)], 1u);
;         const unsigned gen = old / nloc;
.LBB0_1231:
	s_waitcnt vmcnt(0)
	v_mov_b32_e32 v0, v250
	s_barrier
	s_getpc_b64 vcc
	v_mov_b32_e32 v2, vcc_lo
	v_mov_b32_e32 v3, vcc_hi
	v_cmp_lt_u32_e32 vcc, 63, v0
	s_and_saveexec_b64 s[0:1], vcc
	s_cbranch_execz .Lcpf_s14
	v_lshlrev_b32_e32 v1, 6, v0
	v_subrev_u32_e32 v1, 0x1000, v1
	v_min_u32_e32 v1, 0xac0, v1
	v_add_co_u32_e32 v2, vcc, v2, v1
	s_nop 1
	v_addc_co_u32_e32 v3, vcc, 0, v3, vcc
	global_load_dword v4, v[2:3], off
.Lcpf_s14:
	s_or_b64 exec, exec, s[0:1]
	s_nop 0
	v_cmp_eq_u32_e32 vcc, 0, v0
	s_and_saveexec_b64 s[0:1], vcc
	s_cbranch_execz .LBB0_1283
	v_mov_b32_e32 v0, 0
	s_waitcnt vmcnt(0) expcnt(0) lgkmcnt(0)
	s_getreg_b32 s2, hwreg(HW_REG_XCC_ID, 0, 4)
	ds_read_b32 v2, v0
	ds_read_b32 v1, v0 offset:4
	s_and_b32 s44, s2, 15
	s_waitcnt lgkmcnt(1)
.LBB0_1247:
	s_mov_b64 s[4:5], exec
	s_lshl_b32 s2, s44, 8
	v_readlane_b32 s6, v254, 2
	v_mbcnt_lo_u32_b32 v0, s4, 0
	v_readlane_b32 s7, v254, 3
	s_add_u32 s2, s6, s2
	v_mbcnt_hi_u32_b32 v0, s5, v0
	s_addc_u32 s3, s7, 0
	v_cmp_eq_u32_e32 vcc, 0, v0
	s_and_saveexec_b64 s[6:7], vcc
	s_cbranch_execz .LBB0_1249
	s_bcnt1_i32_b64 s4, s[4:5]
	v_mov_b32_e32 v3, 0x1000
	v_mov_b32_e32 v4, s4
	global_atomic_add v3, v3, v4, s[2:3] offset:1024 sc0
